# final_norm row loop: 5 loads per row issued together with counted vmcnt (was 5 serialized round trips per row)
# speedup vs baseline: 1.0600x; 1.0037x over previous
; __device__ __forceinline__ float bf_lo(unsigned w) { return __uint_as_float(w << 16); }
; __device__ __forceinline__ float bf_hi(unsigned w) { return __uint_as_float(w & 0xffff0000u); }
; __device__ __forceinline__ void final_norm(const Params& P) {
;     ...
;     for (int row = gw; row < T_TOK; row += nw) {
;         float t = 0.f; if (lane < 16) t = __uint_as_float(__hip_atomic_load((unsigned*)(ssq0 + ((size_t)(lane >> 2) * T_TOK + row) * 4 + (lane & 3)), __ATOMIC_RELAXED, __HIP_MEMORY_SCOPE_AGENT));
; #pragma unroll
;         for (int o = 8; o >= 1; o >>= 1) t += __shfl_xor(t, o);
;         const float rs = rsqrtf(__shfl(t, 0) * (1.0f / 1024.0f) + 1e-6f);
; #pragma unroll
;         for (int k = 0; k < 4; ++k) { const size_t o = (size_t)row * 1024 + k * 256 + lane * 4; const u32x2 w = *(const u32x2*)(xb0 + o);
;             f32x4 v; v[0] = bf_lo(w.x); v[1] = bf_hi(w.x); v[2] = bf_lo(w.y); v[3] = bf_hi(w.y); *(f32x4*)(P.out + o) = v * rs * g[k]; }
;     }
.LBB0_1350:
	v_readlane_b32 s8, v233, 5
	v_readlane_b32 s9, v233, 6
	v_readlane_b32 s0, v233, 2
	v_ashrrev_i32_e32 v0, 6, v186
	s_nop 0
	v_add_u32_e32 v16, s0, v0
	s_mov_b32 s0, 0x8000
	v_cmp_gt_i32_e32 vcc, s0, v16
	s_and_saveexec_b64 s[0:1], vcc
	s_cbranch_execz .LBB0_1355
	s_load_dwordx4 s[4:7], s[8:9], 0xc0
	s_load_dwordx2 s[2:3], s[8:9], 0xd0
	v_and_b32_e32 v22, 63, v186
	v_lshlrev_b32_e32 v29, 4, v22
	v_lshlrev_b32_e32 v17, 2, v190
	s_waitcnt lgkmcnt(0)
	global_load_dwordx4 v[0:3], v29, s[4:5]
	global_load_dwordx4 v[4:7], v29, s[4:5] offset:1024
	global_load_dwordx4 v[8:11], v29, s[4:5] offset:2048
	global_load_dwordx4 v[12:15], v29, s[4:5] offset:3072
	v_and_b32_e32 v24, 0x100, v17
	v_xor_b32_e32 v17, 8, v190
	v_cmp_lt_i32_e64 s[0:1], v17, v192
	v_mov_b32_e32 v19, 0
	v_and_b32_e32 v20, 3, v186
	v_cndmask_b32_e64 v17, v190, v17, s[0:1]
	v_lshlrev_b32_e32 v25, 2, v17
	v_xor_b32_e32 v17, 4, v190
	v_cmp_lt_i32_e64 s[0:1], v17, v192
	v_cmp_gt_u32_e32 vcc, 16, v22
	s_ashr_i32 s23, s22, 31
	v_cndmask_b32_e64 v17, v190, v17, s[0:1]
	v_lshlrev_b32_e32 v26, 2, v17
	v_xor_b32_e32 v17, 2, v190
	v_cmp_lt_i32_e64 s[0:1], v17, v192
	s_lshl_b64 s[4:5], s[22:23], 4
	s_lshl_b64 s[8:9], s[22:23], 11
	v_cndmask_b32_e64 v17, v190, v17, s[0:1]
	v_cmp_lt_i32_e64 s[0:1], v191, v192
	v_lshlrev_b32_e32 v27, 2, v17
	s_mov_b64 s[10:11], 0
	v_cndmask_b32_e64 v17, v190, v191, s[0:1]
	v_lshlrev_b32_e32 v28, 2, v17
	v_lshlrev_b32_e32 v17, 17, v186
	v_and_b32_e32 v18, 0x180000, v17
	v_ashrrev_i32_e32 v17, 31, v16
	v_lshl_add_u64 v[18:19], v[16:17], 4, v[18:19]
	v_lshl_or_b32 v18, v20, 2, v18
	v_lshlrev_b64 v[20:21], 11, v[16:17]
	v_lshl_or_b32 v20, v22, 3, v20
	v_lshlrev_b64 v[22:23], 12, v[16:17]
	s_mov_b64 s[0:1], 0xa800000
	v_or_b32_e32 v22, v22, v29
	v_lshl_add_u64 v[18:19], v[18:19], 0, s[0:1]
	v_lshl_add_u64 v[22:23], s[6:7], 0, v[22:23]
	s_mov_b64 s[0:1], 0x800
	v_lshl_add_u64 v[22:23], v[22:23], 0, s[0:1]
	s_lshl_b64 s[6:7], s[22:23], 12
	v_mov_b32_e32 v17, 0x358637bd
	s_mov_b32 s12, 0x800000
	s_mov_b32 s13, 0x6800000
	s_movk_i32 s14, 0x7fff
	s_branch .LBB0_1353
.LBB0_1353:
	v_mov_b32_e32 v29, 0
	s_and_saveexec_b64 s[0:1], vcc
	s_cbranch_execz .Lfn_noload
	v_lshl_add_u64 v[30:31], s[2:3], 0, v[18:19]
	global_load_dword v29, v[30:31], off sc1
.Lfn_noload:
	s_or_b64 exec, exec, s[0:1]
	v_lshl_add_u64 v[30:31], s[2:3], 0, v[20:21]
	v_add_co_u32_e64 v34, s[0:1], s13, v30
	s_nop 1
	v_addc_co_u32_e64 v35, s[0:1], 0, v31, s[0:1]
	global_load_dwordx2 v[40:41], v[34:35], off
	global_load_dwordx2 v[42:43], v[34:35], off offset:512
	global_load_dwordx2 v[44:45], v[34:35], off offset:1024
	global_load_dwordx2 v[46:47], v[34:35], off offset:1536
	v_add_u32_e32 v16, s22, v16
	v_lshl_add_u64 v[18:19], v[18:19], 0, s[4:5]
	v_lshl_add_u64 v[20:21], v[20:21], 0, s[8:9]
	v_cmp_lt_i32_e64 s[0:1], s14, v16
	s_or_b64 s[10:11], s[0:1], s[10:11]
	s_waitcnt vmcnt(4)
	ds_bpermute_b32 v32, v25, v29
	s_waitcnt lgkmcnt(0)
	v_add_f32_e32 v29, v29, v32
	ds_bpermute_b32 v32, v26, v29
	s_waitcnt lgkmcnt(0)
	v_add_f32_e32 v29, v29, v32
	ds_bpermute_b32 v32, v27, v29
	s_waitcnt lgkmcnt(0)
	v_add_f32_e32 v29, v29, v32
	ds_bpermute_b32 v32, v28, v29
	s_waitcnt lgkmcnt(0)
	v_add_f32_e32 v29, v29, v32
	ds_bpermute_b32 v29, v24, v29
	s_waitcnt lgkmcnt(0)
	v_fmamk_f32 v29, v29, 0x3a800000, v17
	v_mul_f32_e32 v32, 0x4b800000, v29
	v_cmp_gt_f32_e64 s[0:1], s12, v29
	s_nop 1
	v_cndmask_b32_e64 v29, v29, v32, s[0:1]
	v_rsq_f32_e32 v29, v29
	s_nop 0
	v_mul_f32_e32 v32, 0x45800000, v29
	v_cndmask_b32_e64 v36, v29, v32, s[0:1]
	s_waitcnt vmcnt(3)
	v_lshlrev_b32_e32 v48, 16, v40
	v_and_b32_e32 v49, 0xffff0000, v40
	v_lshlrev_b32_e32 v50, 16, v41
	v_and_b32_e32 v51, 0xffff0000, v41
	v_pk_mul_f32 v[64:65], v[36:37], v[48:49] op_sel_hi:[0,1]
	v_pk_mul_f32 v[50:51], v[36:37], v[50:51] op_sel_hi:[0,1]
	v_pk_mul_f32 v[50:51], v[2:3], v[50:51]
	v_pk_mul_f32 v[48:49], v[0:1], v[64:65]
	global_store_dwordx4 v[22:23], v[48:51], off offset:-2048
	s_waitcnt vmcnt(3)
	v_lshlrev_b32_e32 v52, 16, v42
	v_and_b32_e32 v53, 0xffff0000, v42
	v_lshlrev_b32_e32 v54, 16, v43
	v_and_b32_e32 v55, 0xffff0000, v43
	v_pk_mul_f32 v[66:67], v[36:37], v[52:53] op_sel_hi:[0,1]
	v_pk_mul_f32 v[54:55], v[36:37], v[54:55] op_sel_hi:[0,1]
	v_pk_mul_f32 v[54:55], v[6:7], v[54:55]
	v_pk_mul_f32 v[52:53], v[4:5], v[66:67]
	global_store_dwordx4 v[22:23], v[52:55], off offset:-1024
	s_waitcnt vmcnt(3)
	v_lshlrev_b32_e32 v56, 16, v44
	v_and_b32_e32 v57, 0xffff0000, v44
	v_lshlrev_b32_e32 v58, 16, v45
	v_and_b32_e32 v59, 0xffff0000, v45
	v_pk_mul_f32 v[68:69], v[36:37], v[56:57] op_sel_hi:[0,1]
	v_pk_mul_f32 v[58:59], v[36:37], v[58:59] op_sel_hi:[0,1]
	v_pk_mul_f32 v[58:59], v[10:11], v[58:59]
	v_pk_mul_f32 v[56:57], v[8:9], v[68:69]
	global_store_dwordx4 v[22:23], v[56:59], off
	s_waitcnt vmcnt(3)
	v_lshlrev_b32_e32 v60, 16, v46
	v_and_b32_e32 v61, 0xffff0000, v46
	v_lshlrev_b32_e32 v62, 16, v47
	v_and_b32_e32 v63, 0xffff0000, v47
	v_pk_mul_f32 v[70:71], v[36:37], v[60:61] op_sel_hi:[0,1]
	v_pk_mul_f32 v[62:63], v[36:37], v[62:63] op_sel_hi:[0,1]
	v_pk_mul_f32 v[62:63], v[14:15], v[62:63]
	v_pk_mul_f32 v[60:61], v[12:13], v[70:71]
	global_store_dwordx4 v[22:23], v[60:63], off offset:1024
	v_lshl_add_u64 v[22:23], v[22:23], 0, s[6:7]
	s_andn2_b64 exec, exec, s[10:11]
	s_cbranch_execnz .LBB0_1353
